# grid barrier: last XCD leader bumps all XCD generation words directly; L1 invalidate issued by wave0 at barrier entry (overlaps store drain) instead of after release
# speedup vs baseline: 1.0267x; 1.0211x over previous
; __device__ __forceinline__ void xcd_barrier(const XcdBarrier& b) {
;     asm volatile("s_waitcnt vmcnt(0)" ::: "memory");
;     __syncthreads();
;     int tid0 = threadIdx.x; asm volatile("" : "+v"(tid0));
;     if (tid0 == 0) {
;         unsigned* bar = b.bar;
;         __builtin_amdgcn_s_waitcnt(0);
;         unsigned nloc = b.st[0], nx = b.st[1];
;         if (nloc == 0u) { xcd_barrier_complete(bar, b.x, nloc, nx); b.st[0] = nloc; b.st[1] = nx; }
.LBB0_103:
	s_getreg_b32 s0, hwreg(HW_REG_XCC_ID, 0, 4)
	s_cselect_b32 s99, 1, 0
	v_readfirstlane_b32 s98, v217
	s_cmp_ge_u32 s98, 64
	s_cbranch_scc1 .Lxb_noinv_1
	buffer_inv sc1
.Lxb_noinv_1:
	s_cmp_lg_u32 s99, 0
	s_waitcnt vmcnt(0)
	v_mov_b32_e32 v0, v217
	s_barrier
	s_nop 0
	v_cmp_eq_u32_e32 vcc, 0, v0
	s_and_saveexec_b64 s[2:3], vcc
	s_xor_b64 s[2:3], exec, s[2:3]
	s_cbranch_execz .LBB0_156
	s_lshl_b64 s[4:5], s[4:5], 2
	s_add_u32 s4, s96, s4
	s_addc_u32 s5, s97, s5
	s_add_i32 s1, 0, 0x257f0
	v_mov_b32_e32 v0, s1
	s_waitcnt vmcnt(0) expcnt(0) lgkmcnt(0)
	ds_read_b32 v3, v0
	s_add_i32 s1, 0, 0x257f4
	v_mov_b32_e32 v0, s1
	ds_read_b32 v1, v0
	s_and_b32 s0, s0, 15
	s_waitcnt lgkmcnt(1)
	v_cmp_ne_u32_e32 vcc, 0, v3
	s_cbranch_vccnz .LBB0_119
	v_readlane_b32 s6, v255, 0
	v_readlane_b32 s7, v255, 1
	s_load_dwordx2 s[10:11], s[6:7], 0x4
	s_add_u32 s6, s4, 0x1000
	s_addc_u32 s7, s5, 0
	s_add_u32 s8, s4, 0x1100
	s_addc_u32 s9, s5, 0
	s_waitcnt lgkmcnt(0)
	s_mul_i32 s1, s10, s34
	s_add_u32 s10, s4, 0x1200
	s_mul_i32 s1, s1, s11
	s_addc_u32 s11, s5, 0
	s_add_u32 s12, s4, 0x1300
	s_addc_u32 s13, s5, 0
	s_mov_b32 s18, 1
	v_mov_b32_e32 v18, 0
	s_branch .LBB0_107

; __device__ __forceinline__ unsigned xb_ld(unsigned* p)              { return __hip_atomic_load(p, __ATOMIC_RELAXED, __HIP_MEMORY_SCOPE_AGENT); }
; #define XB_SPIN(cond, bar) do { unsigned _sp = 0; while (cond) { __builtin_amdgcn_s_sleep(1); \
;     if ((++_sp & 255u) == 0u) { if (xb_ld(&(bar)[XB_TMO])) break; if (_sp > XB_SPIN_CAP) { atomicAdd(&(bar)[XB_TMO], 1u); break; } } } } while (0)
; __device__ __forceinline__ void xcd_barrier(const XcdBarrier& b) {
;     ...
;             XB_SPIN(xb_ld(&bar[XB_XGEN(b.x)]) == gen, bar);
;             __builtin_amdgcn_fence(__ATOMIC_ACQUIRE, "agent");
;             asm volatile("s_waitcnt vmcnt(0)" ::: "memory");
.LBB0_134:
	s_or_b64 exec, exec, s[10:11]
	s_waitcnt vmcnt(0) lgkmcnt(0)
	s_waitcnt vmcnt(0)

; __device__ __forceinline__ unsigned xb_add(unsigned* p, unsigned v) { return __hip_atomic_fetch_add(p, v, __ATOMIC_RELAXED, __HIP_MEMORY_SCOPE_AGENT); }
; __device__ __forceinline__ void xcd_barrier(const XcdBarrier& b) {
;     ...
;             __builtin_amdgcn_fence(__ATOMIC_ACQUIRE, "agent");
;             xb_add(&bar[XB_XGEN(b.x)], 1u);
.Lxb_notlast_1:
	s_mov_b64 s[4:5], exec
	v_mbcnt_lo_u32_b32 v0, s4, 0
	v_mbcnt_hi_u32_b32 v0, s5, v0
	v_cmp_eq_u32_e32 vcc, 0, v0
	s_waitcnt vmcnt(0) lgkmcnt(0)
	s_and_saveexec_b64 s[10:11], vcc
	s_cbranch_execz .LBB0_154
	s_bcnt1_i32_b64 s0, s[4:5]
	v_mov_b32_e32 v0, 0x2000
	v_mov_b32_e32 v1, s0

; __device__ __forceinline__ void xcd_barrier(const XcdBarrier& b) {
;     asm volatile("s_waitcnt vmcnt(0)" ::: "memory");
;     __syncthreads();
;     int tid0 = threadIdx.x; asm volatile("" : "+v"(tid0));
;     if (tid0 == 0) {
;         unsigned* bar = b.bar;
;         __builtin_amdgcn_s_waitcnt(0);
;         unsigned nloc = b.st[0], nx = b.st[1];
;         if (nloc == 0u) { xcd_barrier_complete(bar, b.x, nloc, nx); b.st[0] = nloc; b.st[1] = nx; }
.LBB0_186:
	s_mov_b64 s[4:5], 0
	s_getreg_b32 s6, hwreg(HW_REG_XCC_ID, 0, 4)
	s_cselect_b32 s99, 1, 0
	v_readfirstlane_b32 s98, v217
	s_cmp_ge_u32 s98, 64
	s_cbranch_scc1 .Lxb_noinv_2
	buffer_inv sc1
.Lxb_noinv_2:
	s_cmp_lg_u32 s99, 0
	s_waitcnt vmcnt(0)
	v_mov_b32_e32 v2, v217
	s_waitcnt vmcnt(0) lgkmcnt(0)
	s_barrier
	s_nop 0
	v_cmp_eq_u32_e32 vcc, 0, v2
	s_and_saveexec_b64 s[2:3], vcc
	s_xor_b64 s[2:3], exec, s[2:3]
	s_cbranch_execz .LBB0_239
	v_readlane_b32 s7, v255, 23
	s_waitcnt vmcnt(0) expcnt(0) lgkmcnt(0)
	s_lshl_b64 s[4:5], s[4:5], 2
	v_mov_b32_e32 v2, s7
	ds_read_b32 v4, v2
	v_readlane_b32 s7, v255, 24
	s_add_u32 s4, s96, s4
	s_addc_u32 s5, s97, s5
	v_mov_b32_e32 v2, s7
	ds_read_b32 v2, v2
	s_waitcnt lgkmcnt(1)
	v_cmp_ne_u32_e32 vcc, 0, v4
	s_and_b32 s22, s6, 15
	s_cbranch_vccnz .LBB0_202
	v_readlane_b32 s6, v255, 0
	v_readlane_b32 s7, v255, 1
	s_load_dwordx2 s[10:11], s[6:7], 0x4
	s_add_u32 s6, s4, 0x1000
	s_addc_u32 s7, s5, 0
	s_add_u32 s8, s4, 0x1100
	s_addc_u32 s9, s5, 0
	s_waitcnt lgkmcnt(0)
	s_mul_i32 s23, s10, s34
	s_add_u32 s10, s4, 0x1200
	s_mul_i32 s23, s23, s11
	s_addc_u32 s11, s5, 0
	s_add_u32 s12, s4, 0x1300
	s_addc_u32 s13, s5, 0
	s_mov_b32 s24, 1
	s_branch .LBB0_190

; __device__ __forceinline__ unsigned xb_ld(unsigned* p)              { return __hip_atomic_load(p, __ATOMIC_RELAXED, __HIP_MEMORY_SCOPE_AGENT); }
; #define XB_SPIN(cond, bar) do { unsigned _sp = 0; while (cond) { __builtin_amdgcn_s_sleep(1); \
;     if ((++_sp & 255u) == 0u) { if (xb_ld(&(bar)[XB_TMO])) break; if (_sp > XB_SPIN_CAP) { atomicAdd(&(bar)[XB_TMO], 1u); break; } } } } while (0)
; __device__ __forceinline__ void xcd_barrier(const XcdBarrier& b) {
;     ...
;             XB_SPIN(xb_ld(&bar[XB_XGEN(b.x)]) == gen, bar);
;             __builtin_amdgcn_fence(__ATOMIC_ACQUIRE, "agent");
;             asm volatile("s_waitcnt vmcnt(0)" ::: "memory");
.LBB0_217:
	s_or_b64 exec, exec, s[10:11]
	s_waitcnt vmcnt(0)
	s_waitcnt vmcnt(0)

; __device__ __forceinline__ unsigned xb_add(unsigned* p, unsigned v) { return __hip_atomic_fetch_add(p, v, __ATOMIC_RELAXED, __HIP_MEMORY_SCOPE_AGENT); }
; __device__ __forceinline__ void xcd_barrier(const XcdBarrier& b) {
;     ...
;             __builtin_amdgcn_fence(__ATOMIC_ACQUIRE, "agent");
;             xb_add(&bar[XB_XGEN(b.x)], 1u);
.Lxb_notlast_2:
	s_mov_b64 s[4:5], exec
	v_mbcnt_lo_u32_b32 v2, s4, 0
	v_mbcnt_hi_u32_b32 v2, s5, v2
	v_cmp_eq_u32_e32 vcc, 0, v2
	s_waitcnt vmcnt(0)
	s_and_saveexec_b64 s[10:11], vcc
	s_cbranch_execz .LBB0_237
	s_bcnt1_i32_b64 s4, s[4:5]
	v_mov_b32_e32 v2, s4
	v_mov_b32_e32 v3, 0x2000

; __device__ __forceinline__ void xcd_barrier(const XcdBarrier& b) {
;     asm volatile("s_waitcnt vmcnt(0)" ::: "memory");
;     __syncthreads();
;     int tid0 = threadIdx.x; asm volatile("" : "+v"(tid0));
;     if (tid0 == 0) {
;         unsigned* bar = b.bar;
;         __builtin_amdgcn_s_waitcnt(0);
;         unsigned nloc = b.st[0], nx = b.st[1];
;         if (nloc == 0u) { xcd_barrier_complete(bar, b.x, nloc, nx); b.st[0] = nloc; b.st[1] = nx; }
.LBB0_283:
	s_waitcnt lgkmcnt(0)
	s_mov_b64 s[4:5], 0
	s_getreg_b32 s6, hwreg(HW_REG_XCC_ID, 0, 4)
	s_cselect_b32 s99, 1, 0
	v_readfirstlane_b32 s98, v217
	s_cmp_ge_u32 s98, 64
	s_cbranch_scc1 .Lxb_noinv_3
	buffer_inv sc1
.Lxb_noinv_3:
	s_cmp_lg_u32 s99, 0
	s_waitcnt vmcnt(0)
	v_mov_b32_e32 v2, v217
	s_barrier
	s_nop 0
	v_cmp_eq_u32_e32 vcc, 0, v2
	s_and_saveexec_b64 s[2:3], vcc
	s_xor_b64 s[2:3], exec, s[2:3]
	v_readlane_b32 s34, v255, 2
	s_cbranch_execz .LBB0_336
	v_readlane_b32 s7, v255, 23
	s_waitcnt vmcnt(0) expcnt(0) lgkmcnt(0)
	s_lshl_b64 s[4:5], s[4:5], 2
	v_mov_b32_e32 v2, s7
	ds_read_b32 v4, v2
	v_readlane_b32 s7, v255, 24
	s_add_u32 s4, s96, s4
	s_addc_u32 s5, s97, s5
	v_mov_b32_e32 v2, s7
	ds_read_b32 v2, v2
	s_waitcnt lgkmcnt(1)
	v_cmp_ne_u32_e32 vcc, 0, v4
	s_and_b32 s22, s6, 15
	s_cbranch_vccnz .LBB0_299
	v_readlane_b32 s6, v255, 0
	v_readlane_b32 s7, v255, 1
	s_load_dwordx2 s[10:11], s[6:7], 0x4
	s_add_u32 s6, s4, 0x1000
	s_addc_u32 s7, s5, 0
	s_add_u32 s8, s4, 0x1100
	s_addc_u32 s9, s5, 0
	s_waitcnt lgkmcnt(0)
	s_mul_i32 s23, s10, s34
	s_add_u32 s10, s4, 0x1200
	s_mul_i32 s23, s23, s11
	s_addc_u32 s11, s5, 0
	s_add_u32 s12, s4, 0x1300
	s_addc_u32 s13, s5, 0
	s_mov_b32 s24, 1
	s_branch .LBB0_287

; __device__ __forceinline__ void xcd_barrier(const XcdBarrier& b) {
;     asm volatile("s_waitcnt vmcnt(0)" ::: "memory");
;     __syncthreads();
;     int tid0 = threadIdx.x; asm volatile("" : "+v"(tid0));
;     if (tid0 == 0) {
;         unsigned* bar = b.bar;
;         __builtin_amdgcn_s_waitcnt(0);
;         unsigned nloc = b.st[0], nx = b.st[1];
;         if (nloc == 0u) { xcd_barrier_complete(bar, b.x, nloc, nx); b.st[0] = nloc; b.st[1] = nx; }
.Lxb_noinv_4:
	s_cmp_lg_u32 s99, 0
	s_waitcnt vmcnt(0)
	v_mov_b32_e32 v2, v217
	s_waitcnt lgkmcnt(0)
	s_barrier
	s_nop 0
	v_cmp_eq_u32_e32 vcc, 0, v2
	s_and_saveexec_b64 s[2:3], vcc
	v_readlane_b32 s92, v255, 35
	v_readlane_b32 s94, v255, 37
	v_readlane_b32 s96, v255, 39
	v_readlane_b32 s90, v255, 34
	v_readlane_b32 s93, v255, 36
	v_readlane_b32 s95, v255, 38
	v_readlane_b32 s97, v255, 40
	s_cbranch_execz .LBB0_457
	v_readlane_b32 s7, v255, 23
	s_waitcnt vmcnt(0) expcnt(0) lgkmcnt(0)
	s_lshl_b64 s[4:5], s[4:5], 2
	v_mov_b32_e32 v2, s7
	ds_read_b32 v4, v2
	v_readlane_b32 s7, v255, 24
	s_add_u32 s4, s96, s4
	s_addc_u32 s5, s97, s5
	v_mov_b32_e32 v2, s7
	ds_read_b32 v2, v2
	s_waitcnt lgkmcnt(1)
	v_cmp_ne_u32_e32 vcc, 0, v4
	s_and_b32 s22, s6, 15
	s_cbranch_vccnz .LBB0_421
	v_readlane_b32 s6, v255, 0
	v_readlane_b32 s7, v255, 1
	s_load_dwordx2 s[10:11], s[6:7], 0x4
	s_add_u32 s6, s4, 0x1000
	s_addc_u32 s7, s5, 0
	s_add_u32 s8, s4, 0x1100
	s_addc_u32 s9, s5, 0
	s_waitcnt lgkmcnt(0)
	s_mul_i32 s23, s10, s34
	s_add_u32 s10, s4, 0x1200
	s_mul_i32 s23, s23, s11
	s_addc_u32 s11, s5, 0
	s_add_u32 s12, s4, 0x1300
	s_addc_u32 s13, s5, 0
	s_mov_b32 s24, 1
	s_branch .LBB0_409

; __device__ __forceinline__ unsigned xb_add(unsigned* p, unsigned v) { return __hip_atomic_fetch_add(p, v, __ATOMIC_RELAXED, __HIP_MEMORY_SCOPE_AGENT); }
; __device__ __forceinline__ void xcd_barrier(const XcdBarrier& b) {
;     ...
;             __builtin_amdgcn_fence(__ATOMIC_ACQUIRE, "agent");
;             xb_add(&bar[XB_XGEN(b.x)], 1u);
.Lxb_notlast_4:
	s_mov_b64 s[4:5], exec
	v_mbcnt_lo_u32_b32 v2, s4, 0
	v_mbcnt_hi_u32_b32 v2, s5, v2
	v_cmp_eq_u32_e32 vcc, 0, v2
	s_waitcnt vmcnt(0)
	s_and_saveexec_b64 s[8:9], vcc
	s_cbranch_execz .LBB0_456
	s_bcnt1_i32_b64 s4, s[4:5]
	v_mov_b32_e32 v2, s4
	v_mov_b32_e32 v3, 0x2000

; __device__ __forceinline__ void xcd_barrier(const XcdBarrier& b) {
;     asm volatile("s_waitcnt vmcnt(0)" ::: "memory");
;     __syncthreads();
;     int tid0 = threadIdx.x; asm volatile("" : "+v"(tid0));
;     if (tid0 == 0) {
;         unsigned* bar = b.bar;
;         __builtin_amdgcn_s_waitcnt(0);
;         unsigned nloc = b.st[0], nx = b.st[1];
;         if (nloc == 0u) { xcd_barrier_complete(bar, b.x, nloc, nx); b.st[0] = nloc; b.st[1] = nx; }
.Lxb_noinv_5:
	s_cmp_lg_u32 s99, 0
	s_waitcnt vmcnt(0)
	v_mov_b32_e32 v2, v217
	s_barrier
	s_nop 0
	v_cmp_eq_u32_e32 vcc, 0, v2
	s_and_saveexec_b64 s[2:3], vcc
	s_xor_b64 s[2:3], exec, s[2:3]
	s_cbranch_execz .LBB0_516
	v_readlane_b32 s7, v255, 23
	s_waitcnt vmcnt(0) expcnt(0) lgkmcnt(0)
	s_lshl_b64 s[4:5], s[4:5], 2
	v_mov_b32_e32 v2, s7
	ds_read_b32 v4, v2
	v_readlane_b32 s7, v255, 24
	s_add_u32 s4, s96, s4
	s_addc_u32 s5, s97, s5
	v_mov_b32_e32 v2, s7
	ds_read_b32 v2, v2
	s_waitcnt lgkmcnt(1)
	v_cmp_ne_u32_e32 vcc, 0, v4
	s_and_b32 s22, s6, 15
	s_cbranch_vccnz .LBB0_479
	v_readlane_b32 s6, v255, 0
	v_readlane_b32 s7, v255, 1
	s_load_dwordx2 s[10:11], s[6:7], 0x4
	s_add_u32 s6, s4, 0x1000
	s_addc_u32 s7, s5, 0
	s_add_u32 s8, s4, 0x1100
	s_addc_u32 s9, s5, 0
	s_waitcnt lgkmcnt(0)
	s_mul_i32 s23, s10, s34
	s_add_u32 s10, s4, 0x1200
	s_mul_i32 s23, s23, s11
	s_addc_u32 s11, s5, 0
	s_add_u32 s12, s4, 0x1300
	s_addc_u32 s13, s5, 0
	s_mov_b32 s24, 1
	s_branch .LBB0_467

; __device__ __forceinline__ void xcd_barrier(const XcdBarrier& b) {
;     asm volatile("s_waitcnt vmcnt(0)" ::: "memory");
;     __syncthreads();
;     int tid0 = threadIdx.x; asm volatile("" : "+v"(tid0));
;     if (tid0 == 0) {
;         unsigned* bar = b.bar;
;         __builtin_amdgcn_s_waitcnt(0);
;         unsigned nloc = b.st[0], nx = b.st[1];
;         if (nloc == 0u) { xcd_barrier_complete(bar, b.x, nloc, nx); b.st[0] = nloc; b.st[1] = nx; }
.Lxb_noinv_9:
	s_cmp_lg_u32 s99, 0
	s_waitcnt vmcnt(0)
	v_mov_b32_e32 v2, v217
	s_waitcnt lgkmcnt(0)
	s_barrier
	s_nop 0
	v_cmp_eq_u32_e32 vcc, 0, v2
	s_and_saveexec_b64 s[2:3], vcc
	s_xor_b64 s[2:3], exec, s[2:3]
	s_cbranch_execz .LBB0_815
	v_readlane_b32 s7, v255, 23
	s_waitcnt vmcnt(0) expcnt(0) lgkmcnt(0)
	s_lshl_b64 s[4:5], s[4:5], 2
	v_mov_b32_e32 v2, s7
	ds_read_b32 v4, v2
	v_readlane_b32 s7, v255, 24
	s_add_u32 s4, s96, s4
	s_addc_u32 s5, s97, s5
	v_mov_b32_e32 v2, s7
	ds_read_b32 v2, v2
	s_waitcnt lgkmcnt(1)
	v_cmp_ne_u32_e32 vcc, 0, v4
	s_and_b32 s24, s6, 15
	s_cbranch_vccnz .LBB0_778
	v_readlane_b32 s6, v255, 0
	v_readlane_b32 s7, v255, 1
	s_load_dwordx2 s[10:11], s[6:7], 0x4
	s_add_u32 s6, s4, 0x1000
	s_addc_u32 s7, s5, 0
	s_add_u32 s8, s4, 0x1100
	s_addc_u32 s9, s5, 0
	s_waitcnt lgkmcnt(0)
	s_mul_i32 s25, s10, s34
	s_add_u32 s10, s4, 0x1200
	s_mul_i32 s25, s25, s11
	s_addc_u32 s11, s5, 0
	s_add_u32 s12, s4, 0x1300
	s_addc_u32 s13, s5, 0
	s_mov_b32 s26, 1
	s_branch .LBB0_766

; __device__ __forceinline__ void xcd_barrier(const XcdBarrier& b) {
;     asm volatile("s_waitcnt vmcnt(0)" ::: "memory");
;     __syncthreads();
;     int tid0 = threadIdx.x; asm volatile("" : "+v"(tid0));
;     if (tid0 == 0) {
;         unsigned* bar = b.bar;
;         __builtin_amdgcn_s_waitcnt(0);
;         unsigned nloc = b.st[0], nx = b.st[1];
;         if (nloc == 0u) { xcd_barrier_complete(bar, b.x, nloc, nx); b.st[0] = nloc; b.st[1] = nx; }
.Lxb_noinv_10:
	s_cmp_lg_u32 s99, 0
	s_waitcnt vmcnt(0)
	v_mov_b32_e32 v2, v217
	s_waitcnt lgkmcnt(0)
	s_barrier
	s_nop 0
	v_cmp_eq_u32_e32 vcc, 0, v2
	s_and_saveexec_b64 s[2:3], vcc
	s_mov_b32 s22, 0x1000000
	s_cbranch_execz .LBB0_989
	v_readlane_b32 s7, v255, 23
	s_waitcnt vmcnt(0) expcnt(0) lgkmcnt(0)
	s_lshl_b64 s[4:5], s[4:5], 2
	v_mov_b32_e32 v2, s7
	ds_read_b32 v4, v2
	v_readlane_b32 s7, v255, 24
	s_add_u32 s4, s96, s4
	s_addc_u32 s5, s97, s5
	v_mov_b32_e32 v2, s7
	ds_read_b32 v2, v2
	s_waitcnt lgkmcnt(1)
	v_cmp_ne_u32_e32 vcc, 0, v4
	s_and_b32 s22, s6, 15
	s_cbranch_vccnz .LBB0_953
	v_readlane_b32 s6, v255, 0
	v_readlane_b32 s7, v255, 1
	s_load_dwordx2 s[10:11], s[6:7], 0x4
	s_add_u32 s6, s4, 0x1000
	s_addc_u32 s7, s5, 0
	s_add_u32 s8, s4, 0x1100
	s_addc_u32 s9, s5, 0
	s_waitcnt lgkmcnt(0)
	s_mul_i32 s23, s10, s34
	s_add_u32 s10, s4, 0x1200
	s_mul_i32 s23, s23, s11
	s_addc_u32 s11, s5, 0
	s_add_u32 s12, s4, 0x1300
	s_addc_u32 s13, s5, 0
	s_mov_b32 s24, 1
	s_branch .LBB0_941

; __device__ __forceinline__ void xcd_barrier(const XcdBarrier& b) {
;     asm volatile("s_waitcnt vmcnt(0)" ::: "memory");
;     __syncthreads();
;     int tid0 = threadIdx.x; asm volatile("" : "+v"(tid0));
;     if (tid0 == 0) {
;         unsigned* bar = b.bar;
;         __builtin_amdgcn_s_waitcnt(0);
;         unsigned nloc = b.st[0], nx = b.st[1];
;         if (nloc == 0u) { xcd_barrier_complete(bar, b.x, nloc, nx); b.st[0] = nloc; b.st[1] = nx; }
.Lxb_noinv_11:
	s_cmp_lg_u32 s99, 0
	s_waitcnt vmcnt(0)
	v_mov_b32_e32 v2, v217
	s_waitcnt vmcnt(0) lgkmcnt(0)
	s_barrier
	s_nop 0
	v_cmp_eq_u32_e32 vcc, 0, v2
	s_and_saveexec_b64 s[2:3], vcc
	s_cbranch_execz .LBB0_1066
	v_readlane_b32 s7, v255, 23
	s_waitcnt vmcnt(0) expcnt(0) lgkmcnt(0)
	s_lshl_b64 s[4:5], s[4:5], 2
	v_mov_b32_e32 v2, s7
	ds_read_b32 v4, v2
	v_readlane_b32 s7, v255, 24
	s_add_u32 s4, s96, s4
	s_addc_u32 s5, s97, s5
	v_mov_b32_e32 v2, s7
	ds_read_b32 v2, v2
	s_waitcnt lgkmcnt(1)
	v_cmp_ne_u32_e32 vcc, 0, v4
	s_and_b32 s22, s6, 15
	s_cbranch_vccnz .LBB0_1030
	v_readlane_b32 s6, v255, 0
	v_readlane_b32 s7, v255, 1
	s_load_dwordx2 s[10:11], s[6:7], 0x4
	s_add_u32 s6, s4, 0x1000
	s_addc_u32 s7, s5, 0
	s_add_u32 s8, s4, 0x1100
	s_addc_u32 s9, s5, 0
	s_waitcnt lgkmcnt(0)
	s_mul_i32 s23, s10, s34
	s_add_u32 s10, s4, 0x1200
	s_mul_i32 s23, s23, s11
	s_addc_u32 s11, s5, 0
	s_add_u32 s12, s4, 0x1300
	s_addc_u32 s13, s5, 0
	s_mov_b32 s24, 1
	s_branch .LBB0_1018
